# out-proj K-loops too: first K-iteration peeled with srcC = 0, per-unit accumulator zeroing deleted (all six fp8 GEMM loops now)
# speedup vs baseline: 1.0031x; 1.0031x over previous
.LBB0_1272:
	s_add_u32 s31, s44, 0x80000
	s_addc_u32 s48, s45, 0
	s_add_u32 s42, s42, 0x40080
	s_addc_u32 s43, s43, 0
	s_mov_b32 s49, -2
	ds_read_b128 v[130:133], v146
	ds_read_b128 v[134:137], v146 offset:1024
	ds_read_b128 v[150:153], v146 offset:2048
	ds_read_b128 v[154:157], v146 offset:3072
	ds_read_b128 v[158:161], v147
	ds_read_b128 v[162:165], v147 offset:1024
	ds_read_b128 v[166:169], v147 offset:2048
	ds_read_b128 v[170:173], v147 offset:3072
	s_add_u32 s44, s42, 0xfffc0080
	s_addc_u32 s45, s43, -1
	s_cmp_eq_u32 s49, 12
	s_cselect_b32 s45, s35, s45
	s_cselect_b32 s44, s34, s44
	s_cselect_b32 s47, s37, s48
	s_cselect_b32 s46, s36, s31
	v_mov_b32_e32 v128, v142
	v_mov_b32_e32 v138, v141
	s_add_i32 m0, s53, 0xc000
	ds_read_b128 v[174:177], v148
	ds_read_b128 v[178:181], v148 offset:1024
	ds_read_b128 v[182:185], v148 offset:2048
	ds_read_b128 v[186:189], v148 offset:3072
	ds_read_b128 v[190:193], v148 offset:4096
	ds_read_b128 v[194:197], v148 offset:5120
	ds_read_b128 v[198:201], v148 offset:6144
	ds_read_b128 v[202:205], v148 offset:7168
	s_nop 0
	global_load_lds_dwordx4 v138, s[42:43]
	s_add_i32 m0, s53, 0xe000
	s_nop 0
	global_load_lds_dwordx4 v128, s[42:43]
	s_and_b64 vcc, exec, s[20:21]
	s_cbranch_vccnz .Lmy_p1lw_1
	s_waitcnt vmcnt(8)
.Lmy_p1lw_1:
	s_waitcnt lgkmcnt(0)
	s_barrier
	s_setprio 1
	s_waitcnt lgkmcnt(0)
	v_mfma_scale_f32_16x16x128_f8f6f4 v[124:127], v[130:137], v[174:181], 0, v149, v149 op_sel_hi:[0,0,0]
	v_mfma_scale_f32_16x16x128_f8f6f4 v[120:123], v[150:157], v[174:181], 0, v149, v149 op_sel_hi:[0,0,0]
	v_mfma_scale_f32_16x16x128_f8f6f4 v[108:111], v[130:137], v[182:189], 0, v149, v149 op_sel_hi:[0,0,0]
	v_mfma_scale_f32_16x16x128_f8f6f4 v[104:107], v[150:157], v[182:189], 0, v149, v149 op_sel_hi:[0,0,0]
	v_mfma_scale_f32_16x16x128_f8f6f4 v[206:209], v[130:137], v[190:197], 0, v149, v149 op_sel_hi:[0,0,0]
	v_mfma_scale_f32_16x16x128_f8f6f4 v[214:217], v[150:157], v[190:197], 0, v149, v149 op_sel_hi:[0,0,0]
	v_mfma_scale_f32_16x16x128_f8f6f4 v[218:221], v[130:137], v[198:205], 0, v149, v149 op_sel_hi:[0,0,0]
	v_mfma_scale_f32_16x16x128_f8f6f4 v[222:225], v[150:157], v[198:205], 0, v149, v149 op_sel_hi:[0,0,0]
	s_setprio 0
	s_setprio 1
	v_mfma_scale_f32_16x16x128_f8f6f4 v[116:119], v[158:165], v[174:181], 0, v149, v149 op_sel_hi:[0,0,0]
	v_mfma_scale_f32_16x16x128_f8f6f4 v[112:115], v[166:173], v[174:181], 0, v149, v149 op_sel_hi:[0,0,0]
	v_mfma_scale_f32_16x16x128_f8f6f4 v[100:103], v[158:165], v[182:189], 0, v149, v149 op_sel_hi:[0,0,0]
	v_mfma_scale_f32_16x16x128_f8f6f4 v[96:99], v[166:173], v[182:189], 0, v149, v149 op_sel_hi:[0,0,0]
	v_mfma_scale_f32_16x16x128_f8f6f4 v[174:177], v[158:165], v[190:197], 0, v149, v149 op_sel_hi:[0,0,0]
	v_mfma_scale_f32_16x16x128_f8f6f4 v[178:181], v[166:173], v[190:197], 0, v149, v149 op_sel_hi:[0,0,0]
	v_mfma_scale_f32_16x16x128_f8f6f4 v[182:185], v[158:165], v[198:205], 0, v149, v149 op_sel_hi:[0,0,0]
	v_mfma_scale_f32_16x16x128_f8f6f4 v[186:189], v[166:173], v[198:205], 0, v149, v149 op_sel_hi:[0,0,0]
	s_setprio 0
	s_waitcnt vmcnt(8)
	s_barrier
	s_add_i32 s64, s71, s3
	v_mov_b32_e32 v128, v144
	v_mov_b32_e32 v138, v143
	s_mov_b32 m0, s64
	s_nop 0
	ds_read_b128 v[64:67], v148 offset:16384
	ds_read_b128 v[68:71], v148 offset:17408
	ds_read_b128 v[72:75], v148 offset:18432
	ds_read_b128 v[76:79], v148 offset:19456
	ds_read_b128 v[80:83], v148 offset:20480
	ds_read_b128 v[84:87], v148 offset:21504
	ds_read_b128 v[88:91], v148 offset:22528
	ds_read_b128 v[92:95], v148 offset:23552
	v_mov_b32_e32 v139, v129
	global_load_lds_dwordx4 v138, s[46:47]
	s_add_i32 m0, s64, 0x2000
	v_mov_b32_e32 v138, v144
	global_load_lds_dwordx4 v128, s[46:47]
	v_mov_b32_e32 v128, v143
	s_add_i32 s64, s72, s3
	v_lshl_add_u64 v[190:191], s[46:47], 0, v[128:129]
	v_lshl_add_u64 v[190:191], v[190:191], 0, s[14:15]
	s_mov_b32 m0, s64
	v_lshl_add_u64 v[138:139], s[46:47], 0, v[138:139]
	global_load_lds_dwordx4 v[190:191], off
	v_lshl_add_u64 v[138:139], v[138:139], 0, s[14:15]
	s_add_i32 m0, s64, 0x2000
	v_mov_b32_e32 v128, v142
	global_load_lds_dwordx4 v[138:139], off
	v_mov_b32_e32 v138, v141
	s_mov_b32 m0, s53
	s_nop 0
	global_load_lds_dwordx4 v138, s[44:45]
	s_mov_b32 m0, s54
	s_nop 0
	global_load_lds_dwordx4 v128, s[44:45]
	s_and_b64 vcc, exec, s[20:21]
	s_cbranch_vccnz .Lmy_p1lw_2
	s_waitcnt vmcnt(8)
.Lmy_p1lw_2:
	s_waitcnt lgkmcnt(0)
	s_barrier
	s_setprio 1
	s_waitcnt lgkmcnt(0)
	v_mfma_scale_f32_16x16x128_f8f6f4 v[60:63], v[130:137], v[64:71], 0, v149, v149 op_sel_hi:[0,0,0]
	v_mfma_scale_f32_16x16x128_f8f6f4 v[56:59], v[150:157], v[64:71], 0, v149, v149 op_sel_hi:[0,0,0]
	v_mfma_scale_f32_16x16x128_f8f6f4 v[190:193], v[130:137], v[72:79], 0, v149, v149 op_sel_hi:[0,0,0]
	v_mfma_scale_f32_16x16x128_f8f6f4 v[194:197], v[150:157], v[72:79], 0, v149, v149 op_sel_hi:[0,0,0]
	v_mfma_scale_f32_16x16x128_f8f6f4 v[198:201], v[130:137], v[80:87], 0, v149, v149 op_sel_hi:[0,0,0]
	v_mfma_scale_f32_16x16x128_f8f6f4 v[202:205], v[150:157], v[80:87], 0, v149, v149 op_sel_hi:[0,0,0]
	v_mfma_scale_f32_16x16x128_f8f6f4 v[226:229], v[130:137], v[88:95], 0, v149, v149 op_sel_hi:[0,0,0]
	v_mfma_scale_f32_16x16x128_f8f6f4 v[230:233], v[150:157], v[88:95], 0, v149, v149 op_sel_hi:[0,0,0]
	s_setprio 0
	s_setprio 1
	v_mfma_scale_f32_16x16x128_f8f6f4 v[52:55], v[158:165], v[64:71], 0, v149, v149 op_sel_hi:[0,0,0]
	v_mfma_scale_f32_16x16x128_f8f6f4 v[48:51], v[166:173], v[64:71], 0, v149, v149 op_sel_hi:[0,0,0]
	v_mfma_scale_f32_16x16x128_f8f6f4 v[234:237], v[158:165], v[72:79], 0, v149, v149 op_sel_hi:[0,0,0]
	v_mfma_scale_f32_16x16x128_f8f6f4 v[238:241], v[166:173], v[72:79], 0, v149, v149 op_sel_hi:[0,0,0]
	v_mfma_scale_f32_16x16x128_f8f6f4 v[242:245], v[158:165], v[80:87], 0, v149, v149 op_sel_hi:[0,0,0]
	v_mfma_scale_f32_16x16x128_f8f6f4 v[246:249], v[166:173], v[80:87], 0, v149, v149 op_sel_hi:[0,0,0]
	v_mfma_scale_f32_16x16x128_f8f6f4 v[250:253], v[158:165], v[88:95], 0, v149, v149 op_sel_hi:[0,0,0]
	v_mfma_scale_f32_16x16x128_f8f6f4 v[210:213], v[166:173], v[88:95], 0, v149, v149 op_sel_hi:[0,0,0]
	s_setprio 0
	s_waitcnt vmcnt(8)
	s_barrier
	s_add_i32 s77, 0, 0x18000
	v_add_u32_e32 v8, s77, v145
	s_add_i32 s78, 0, 0x1c000
	s_nop 1
	ds_read_b128 v[0:3], v8
	ds_read_b128 v[4:7], v8 offset:1024
	ds_read_b128 v[16:19], v8 offset:2048
	ds_read_b128 v[20:23], v8 offset:3072
	v_add_u32_e32 v8, s78, v145
	ds_read_b128 v[130:133], v8
	ds_read_b128 v[134:137], v8 offset:1024
	ds_read_b128 v[150:153], v8 offset:2048
	ds_read_b128 v[154:157], v8 offset:3072
	s_add_u32 s64, s44, 0x40000
	v_mov_b32_e32 v64, v142
	v_mov_b32_e32 v65, v141
	s_addc_u32 s65, s45, 0
	s_mov_b32 m0, s55
	ds_read_b128 v[8:11], v148 offset:32768
	ds_read_b128 v[12:15], v148 offset:33792
	ds_read_b128 v[24:27], v148 offset:34816
	ds_read_b128 v[28:31], v148 offset:35840
	ds_read_b128 v[32:35], v148 offset:36864
	ds_read_b128 v[36:39], v148 offset:37888
	ds_read_b128 v[40:43], v148 offset:38912
	ds_read_b128 v[44:47], v148 offset:39936
	s_nop 0
	global_load_lds_dwordx4 v65, s[64:65]
	s_mov_b32 m0, s63
	s_nop 0
	global_load_lds_dwordx4 v64, s[64:65]
	s_and_b64 vcc, exec, s[20:21]
	s_cbranch_vccnz .Lmy_p1lw_3
	s_waitcnt vmcnt(8)

.Lmy_p1lw_4:
	s_waitcnt lgkmcnt(0)
	s_barrier
	s_setprio 1
	s_waitcnt lgkmcnt(0)
	v_mfma_scale_f32_16x16x128_f8f6f4 v[60:63], v[0:7], v[32:39], v[60:63], v149, v149 op_sel_hi:[0,0,0]
	v_mfma_scale_f32_16x16x128_f8f6f4 v[56:59], v[16:23], v[32:39], v[56:59], v149, v149 op_sel_hi:[0,0,0]
	v_mfma_scale_f32_16x16x128_f8f6f4 v[44:47], v[0:7], v[158:165], v[190:193], v149, v149 op_sel_hi:[0,0,0]
	v_mfma_scale_f32_16x16x128_f8f6f4 v[40:43], v[16:23], v[158:165], v[194:197], v149, v149 op_sel_hi:[0,0,0]
	v_mfma_scale_f32_16x16x128_f8f6f4 v[28:31], v[0:7], v[166:173], v[198:201], v149, v149 op_sel_hi:[0,0,0]
	v_mfma_scale_f32_16x16x128_f8f6f4 v[24:27], v[16:23], v[166:173], v[202:205], v149, v149 op_sel_hi:[0,0,0]
	v_mfma_scale_f32_16x16x128_f8f6f4 v[12:15], v[0:7], v[174:181], v[226:229], v149, v149 op_sel_hi:[0,0,0]
	v_mfma_scale_f32_16x16x128_f8f6f4 v[8:11], v[16:23], v[174:181], v[230:233], v149, v149 op_sel_hi:[0,0,0]
	s_setprio 0
	s_setprio 1
	v_mfma_scale_f32_16x16x128_f8f6f4 v[52:55], v[130:137], v[32:39], v[52:55], v149, v149 op_sel_hi:[0,0,0]
	v_mfma_scale_f32_16x16x128_f8f6f4 v[48:51], v[150:157], v[32:39], v[48:51], v149, v149 op_sel_hi:[0,0,0]
	v_mfma_scale_f32_16x16x128_f8f6f4 v[36:39], v[130:137], v[158:165], v[234:237], v149, v149 op_sel_hi:[0,0,0]
	v_mfma_scale_f32_16x16x128_f8f6f4 v[32:35], v[150:157], v[158:165], v[238:241], v149, v149 op_sel_hi:[0,0,0]
	v_mfma_scale_f32_16x16x128_f8f6f4 v[20:23], v[130:137], v[166:173], v[242:245], v149, v149 op_sel_hi:[0,0,0]
	v_mfma_scale_f32_16x16x128_f8f6f4 v[16:19], v[150:157], v[166:173], v[246:249], v149, v149 op_sel_hi:[0,0,0]
	v_mfma_scale_f32_16x16x128_f8f6f4 v[4:7], v[130:137], v[174:181], v[250:253], v149, v149 op_sel_hi:[0,0,0]
	v_mfma_scale_f32_16x16x128_f8f6f4 v[0:3], v[150:157], v[174:181], v[210:213], v149, v149 op_sel_hi:[0,0,0]
	s_setprio 0
	s_waitcnt vmcnt(8)
	s_barrier
	s_add_i32 s49, s49, 2
	s_add_u32 s31, s31, 0x80000
	s_addc_u32 s48, s48, 0
	s_add_u32 s42, s42, 0x100
	s_addc_u32 s43, s43, 0
	s_cmp_gt_u32 s49, 13
.LBB0_1273:
	ds_read_b128 v[130:133], v146
	ds_read_b128 v[134:137], v146 offset:1024
	ds_read_b128 v[150:153], v146 offset:2048
	ds_read_b128 v[154:157], v146 offset:3072
	ds_read_b128 v[158:161], v147
	ds_read_b128 v[162:165], v147 offset:1024
	ds_read_b128 v[166:169], v147 offset:2048
	ds_read_b128 v[170:173], v147 offset:3072
	s_add_u32 s44, s42, 0xfffc0080
	s_addc_u32 s45, s43, -1
	s_cmp_eq_u32 s49, 12
	s_cselect_b32 s45, s35, s45
	s_cselect_b32 s44, s34, s44
	s_cselect_b32 s47, s37, s48
	s_cselect_b32 s46, s36, s31
	v_mov_b32_e32 v128, v142
	v_mov_b32_e32 v138, v141
	s_add_i32 m0, s53, 0xc000
	ds_read_b128 v[174:177], v148
	ds_read_b128 v[178:181], v148 offset:1024
	ds_read_b128 v[182:185], v148 offset:2048
	ds_read_b128 v[186:189], v148 offset:3072
	ds_read_b128 v[190:193], v148 offset:4096
	ds_read_b128 v[194:197], v148 offset:5120
	ds_read_b128 v[198:201], v148 offset:6144
	ds_read_b128 v[202:205], v148 offset:7168
	s_nop 0
	global_load_lds_dwordx4 v138, s[42:43]
	s_add_i32 m0, s53, 0xe000
	s_nop 0
	global_load_lds_dwordx4 v128, s[42:43]
	s_and_b64 vcc, exec, s[20:21]
	s_cbranch_vccnz .Lmy_lw_1
	s_waitcnt vmcnt(8)

.LBB0_2486:
	s_add_u32 s29, s42, 0x80000
	s_addc_u32 s48, s43, 0
	s_add_u32 s40, s40, 0x40080
	s_addc_u32 s41, s41, 0
	s_mov_b32 s49, -2
	ds_read_b128 v[130:133], v146
	ds_read_b128 v[134:137], v146 offset:1024
	ds_read_b128 v[150:153], v146 offset:2048
	ds_read_b128 v[154:157], v146 offset:3072
	ds_read_b128 v[158:161], v147
	ds_read_b128 v[162:165], v147 offset:1024
	ds_read_b128 v[166:169], v147 offset:2048
	ds_read_b128 v[170:173], v147 offset:3072
	s_add_u32 s42, s40, 0xfffc0080
	s_addc_u32 s43, s41, -1
	s_cmp_eq_u32 s49, 12
	s_cselect_b32 s43, s31, s43
	s_cselect_b32 s42, s30, s42
	s_cselect_b32 s45, s35, s48
	s_cselect_b32 s44, s34, s29
	v_mov_b32_e32 v128, v142
	v_mov_b32_e32 v138, v141
	s_add_i32 m0, s47, 0xc000
	ds_read_b128 v[174:177], v148
	ds_read_b128 v[178:181], v148 offset:1024
	ds_read_b128 v[182:185], v148 offset:2048
	ds_read_b128 v[186:189], v148 offset:3072
	ds_read_b128 v[190:193], v148 offset:4096
	ds_read_b128 v[194:197], v148 offset:5120
	ds_read_b128 v[198:201], v148 offset:6144
	ds_read_b128 v[202:205], v148 offset:7168
	s_nop 0
	global_load_lds_dwordx4 v138, s[40:41]
	s_add_i32 m0, s47, 0xe000
	s_nop 0
	global_load_lds_dwordx4 v128, s[40:41]
	s_and_b64 vcc, exec, s[16:17]
	s_cbranch_vccnz .Lmy_p2lw_13
	s_waitcnt vmcnt(8)
.Lmy_p2lw_13:
	s_waitcnt lgkmcnt(0)
	s_barrier
	s_setprio 1
	s_waitcnt lgkmcnt(0)
	v_mfma_scale_f32_16x16x128_f8f6f4 v[124:127], v[130:137], v[174:181], 0, v149, v149 op_sel_hi:[0,0,0]
	v_mfma_scale_f32_16x16x128_f8f6f4 v[120:123], v[150:157], v[174:181], 0, v149, v149 op_sel_hi:[0,0,0]
	v_mfma_scale_f32_16x16x128_f8f6f4 v[108:111], v[130:137], v[182:189], 0, v149, v149 op_sel_hi:[0,0,0]
	v_mfma_scale_f32_16x16x128_f8f6f4 v[104:107], v[150:157], v[182:189], 0, v149, v149 op_sel_hi:[0,0,0]
	v_mfma_scale_f32_16x16x128_f8f6f4 v[206:209], v[130:137], v[190:197], 0, v149, v149 op_sel_hi:[0,0,0]
	v_mfma_scale_f32_16x16x128_f8f6f4 v[210:213], v[150:157], v[190:197], 0, v149, v149 op_sel_hi:[0,0,0]
	v_mfma_scale_f32_16x16x128_f8f6f4 v[214:217], v[130:137], v[198:205], 0, v149, v149 op_sel_hi:[0,0,0]
	v_mfma_scale_f32_16x16x128_f8f6f4 v[218:221], v[150:157], v[198:205], 0, v149, v149 op_sel_hi:[0,0,0]
	s_setprio 0
	s_setprio 1
	v_mfma_scale_f32_16x16x128_f8f6f4 v[116:119], v[158:165], v[174:181], 0, v149, v149 op_sel_hi:[0,0,0]
	v_mfma_scale_f32_16x16x128_f8f6f4 v[112:115], v[166:173], v[174:181], 0, v149, v149 op_sel_hi:[0,0,0]
	v_mfma_scale_f32_16x16x128_f8f6f4 v[100:103], v[158:165], v[182:189], 0, v149, v149 op_sel_hi:[0,0,0]
	v_mfma_scale_f32_16x16x128_f8f6f4 v[96:99], v[166:173], v[182:189], 0, v149, v149 op_sel_hi:[0,0,0]
	v_mfma_scale_f32_16x16x128_f8f6f4 v[174:177], v[158:165], v[190:197], 0, v149, v149 op_sel_hi:[0,0,0]
	v_mfma_scale_f32_16x16x128_f8f6f4 v[178:181], v[166:173], v[190:197], 0, v149, v149 op_sel_hi:[0,0,0]
	v_mfma_scale_f32_16x16x128_f8f6f4 v[182:185], v[158:165], v[198:205], 0, v149, v149 op_sel_hi:[0,0,0]
	v_mfma_scale_f32_16x16x128_f8f6f4 v[186:189], v[166:173], v[198:205], 0, v149, v149 op_sel_hi:[0,0,0]
	s_setprio 0
	s_waitcnt vmcnt(8)
	s_barrier
	s_add_i32 s64, s67, s3
	v_mov_b32_e32 v128, v144
	v_mov_b32_e32 v138, v143
	s_mov_b32 m0, s64
	s_nop 0
	ds_read_b128 v[64:67], v148 offset:16384
	ds_read_b128 v[68:71], v148 offset:17408
	ds_read_b128 v[72:75], v148 offset:18432
	ds_read_b128 v[76:79], v148 offset:19456
	ds_read_b128 v[80:83], v148 offset:20480
	ds_read_b128 v[84:87], v148 offset:21504
	ds_read_b128 v[88:91], v148 offset:22528
	ds_read_b128 v[92:95], v148 offset:23552
	v_mov_b32_e32 v139, v129
	global_load_lds_dwordx4 v138, s[44:45]
	s_add_i32 m0, s64, 0x2000
	v_mov_b32_e32 v138, v144
	global_load_lds_dwordx4 v128, s[44:45]
	v_mov_b32_e32 v128, v143
	s_add_i32 s64, s68, s3
	v_lshl_add_u64 v[190:191], s[44:45], 0, v[128:129]
	v_lshl_add_u64 v[190:191], v[190:191], 0, s[10:11]
	s_mov_b32 m0, s64
	v_lshl_add_u64 v[138:139], s[44:45], 0, v[138:139]
	global_load_lds_dwordx4 v[190:191], off
	v_lshl_add_u64 v[138:139], v[138:139], 0, s[10:11]
	s_add_i32 m0, s64, 0x2000
	v_mov_b32_e32 v128, v142
	global_load_lds_dwordx4 v[138:139], off
	v_mov_b32_e32 v138, v141
	s_mov_b32 m0, s47
	s_nop 0
	global_load_lds_dwordx4 v138, s[42:43]
	s_mov_b32 m0, s50
	s_nop 0
	global_load_lds_dwordx4 v128, s[42:43]
	s_and_b64 vcc, exec, s[16:17]
	s_cbranch_vccnz .Lmy_p2lw_14
	s_waitcnt vmcnt(8)
.Lmy_p2lw_14:
	s_waitcnt lgkmcnt(0)
	s_barrier
	s_setprio 1
	s_waitcnt lgkmcnt(0)
	v_mfma_scale_f32_16x16x128_f8f6f4 v[60:63], v[130:137], v[64:71], 0, v149, v149 op_sel_hi:[0,0,0]
	v_mfma_scale_f32_16x16x128_f8f6f4 v[56:59], v[150:157], v[64:71], 0, v149, v149 op_sel_hi:[0,0,0]
	v_mfma_scale_f32_16x16x128_f8f6f4 v[190:193], v[130:137], v[72:79], 0, v149, v149 op_sel_hi:[0,0,0]
	v_mfma_scale_f32_16x16x128_f8f6f4 v[194:197], v[150:157], v[72:79], 0, v149, v149 op_sel_hi:[0,0,0]
	v_mfma_scale_f32_16x16x128_f8f6f4 v[198:201], v[130:137], v[80:87], 0, v149, v149 op_sel_hi:[0,0,0]
	v_mfma_scale_f32_16x16x128_f8f6f4 v[202:205], v[150:157], v[80:87], 0, v149, v149 op_sel_hi:[0,0,0]
	v_mfma_scale_f32_16x16x128_f8f6f4 v[222:225], v[130:137], v[88:95], 0, v149, v149 op_sel_hi:[0,0,0]
	v_mfma_scale_f32_16x16x128_f8f6f4 v[226:229], v[150:157], v[88:95], 0, v149, v149 op_sel_hi:[0,0,0]
	s_setprio 0
	s_setprio 1
	v_mfma_scale_f32_16x16x128_f8f6f4 v[52:55], v[158:165], v[64:71], 0, v149, v149 op_sel_hi:[0,0,0]
	v_mfma_scale_f32_16x16x128_f8f6f4 v[48:51], v[166:173], v[64:71], 0, v149, v149 op_sel_hi:[0,0,0]
	v_mfma_scale_f32_16x16x128_f8f6f4 v[230:233], v[158:165], v[72:79], 0, v149, v149 op_sel_hi:[0,0,0]
	v_mfma_scale_f32_16x16x128_f8f6f4 v[234:237], v[166:173], v[72:79], 0, v149, v149 op_sel_hi:[0,0,0]
	v_mfma_scale_f32_16x16x128_f8f6f4 v[238:241], v[158:165], v[80:87], 0, v149, v149 op_sel_hi:[0,0,0]
	v_mfma_scale_f32_16x16x128_f8f6f4 v[242:245], v[166:173], v[80:87], 0, v149, v149 op_sel_hi:[0,0,0]
	v_mfma_scale_f32_16x16x128_f8f6f4 v[246:249], v[158:165], v[88:95], 0, v149, v149 op_sel_hi:[0,0,0]
	v_mfma_scale_f32_16x16x128_f8f6f4 v[250:253], v[166:173], v[88:95], 0, v149, v149 op_sel_hi:[0,0,0]
	s_setprio 0
	s_waitcnt vmcnt(8)
	s_barrier
	s_add_i32 s73, 0, 0x18000
	v_add_u32_e32 v8, s73, v145
	s_add_i32 s74, 0, 0x1c000
	s_nop 1
	ds_read_b128 v[0:3], v8
	ds_read_b128 v[4:7], v8 offset:1024
	ds_read_b128 v[16:19], v8 offset:2048
	ds_read_b128 v[20:23], v8 offset:3072
	v_add_u32_e32 v8, s74, v145
	ds_read_b128 v[130:133], v8
	ds_read_b128 v[134:137], v8 offset:1024
	ds_read_b128 v[150:153], v8 offset:2048
	ds_read_b128 v[154:157], v8 offset:3072
	s_add_u32 s64, s42, 0x40000
	v_mov_b32_e32 v64, v142
	v_mov_b32_e32 v65, v141
	s_addc_u32 s65, s43, 0
	s_mov_b32 m0, s51
	ds_read_b128 v[8:11], v148 offset:32768
	ds_read_b128 v[12:15], v148 offset:33792
	ds_read_b128 v[24:27], v148 offset:34816
	ds_read_b128 v[28:31], v148 offset:35840
	ds_read_b128 v[32:35], v148 offset:36864
	ds_read_b128 v[36:39], v148 offset:37888
	ds_read_b128 v[40:43], v148 offset:38912
	ds_read_b128 v[44:47], v148 offset:39936
	s_nop 0
	global_load_lds_dwordx4 v65, s[64:65]
	s_mov_b32 m0, s52
	s_nop 0
	global_load_lds_dwordx4 v64, s[64:65]
	s_and_b64 vcc, exec, s[16:17]
	s_cbranch_vccnz .Lmy_p2lw_15
	s_waitcnt vmcnt(8)

.Lmy_p2lw_16:
	s_waitcnt lgkmcnt(0)
	s_barrier
	s_setprio 1
	s_waitcnt lgkmcnt(0)
	v_mfma_scale_f32_16x16x128_f8f6f4 v[60:63], v[0:7], v[32:39], v[60:63], v149, v149 op_sel_hi:[0,0,0]
	v_mfma_scale_f32_16x16x128_f8f6f4 v[56:59], v[16:23], v[32:39], v[56:59], v149, v149 op_sel_hi:[0,0,0]
	v_mfma_scale_f32_16x16x128_f8f6f4 v[44:47], v[0:7], v[158:165], v[190:193], v149, v149 op_sel_hi:[0,0,0]
	v_mfma_scale_f32_16x16x128_f8f6f4 v[40:43], v[16:23], v[158:165], v[194:197], v149, v149 op_sel_hi:[0,0,0]
	v_mfma_scale_f32_16x16x128_f8f6f4 v[28:31], v[0:7], v[166:173], v[198:201], v149, v149 op_sel_hi:[0,0,0]
	v_mfma_scale_f32_16x16x128_f8f6f4 v[24:27], v[16:23], v[166:173], v[202:205], v149, v149 op_sel_hi:[0,0,0]
	v_mfma_scale_f32_16x16x128_f8f6f4 v[12:15], v[0:7], v[174:181], v[222:225], v149, v149 op_sel_hi:[0,0,0]
	v_mfma_scale_f32_16x16x128_f8f6f4 v[8:11], v[16:23], v[174:181], v[226:229], v149, v149 op_sel_hi:[0,0,0]
	s_setprio 0
	s_setprio 1
	v_mfma_scale_f32_16x16x128_f8f6f4 v[52:55], v[130:137], v[32:39], v[52:55], v149, v149 op_sel_hi:[0,0,0]
	v_mfma_scale_f32_16x16x128_f8f6f4 v[48:51], v[150:157], v[32:39], v[48:51], v149, v149 op_sel_hi:[0,0,0]
	v_mfma_scale_f32_16x16x128_f8f6f4 v[36:39], v[130:137], v[158:165], v[230:233], v149, v149 op_sel_hi:[0,0,0]
	v_mfma_scale_f32_16x16x128_f8f6f4 v[32:35], v[150:157], v[158:165], v[234:237], v149, v149 op_sel_hi:[0,0,0]
	v_mfma_scale_f32_16x16x128_f8f6f4 v[20:23], v[130:137], v[166:173], v[238:241], v149, v149 op_sel_hi:[0,0,0]
	v_mfma_scale_f32_16x16x128_f8f6f4 v[16:19], v[150:157], v[166:173], v[242:245], v149, v149 op_sel_hi:[0,0,0]
	v_mfma_scale_f32_16x16x128_f8f6f4 v[4:7], v[130:137], v[174:181], v[246:249], v149, v149 op_sel_hi:[0,0,0]
	v_mfma_scale_f32_16x16x128_f8f6f4 v[0:3], v[150:157], v[174:181], v[250:253], v149, v149 op_sel_hi:[0,0,0]
	s_setprio 0
	s_waitcnt vmcnt(8)
	s_barrier
	s_add_i32 s49, s49, 2
	s_add_u32 s29, s29, 0x80000
	s_addc_u32 s48, s48, 0
	s_add_u32 s40, s40, 0x100
	s_addc_u32 s41, s41, 0
	s_cmp_gt_u32 s49, 13
.LBB0_2487:
	ds_read_b128 v[130:133], v146
	ds_read_b128 v[134:137], v146 offset:1024
	ds_read_b128 v[150:153], v146 offset:2048
	ds_read_b128 v[154:157], v146 offset:3072
	ds_read_b128 v[158:161], v147
	ds_read_b128 v[162:165], v147 offset:1024
	ds_read_b128 v[166:169], v147 offset:2048
	ds_read_b128 v[170:173], v147 offset:3072
	s_add_u32 s42, s40, 0xfffc0080
	s_addc_u32 s43, s41, -1
	s_cmp_eq_u32 s49, 12
	s_cselect_b32 s43, s31, s43
	s_cselect_b32 s42, s30, s42
	s_cselect_b32 s45, s35, s48
	s_cselect_b32 s44, s34, s29
	v_mov_b32_e32 v128, v142
	v_mov_b32_e32 v138, v141
	s_add_i32 m0, s47, 0xc000
	ds_read_b128 v[174:177], v148
	ds_read_b128 v[178:181], v148 offset:1024
	ds_read_b128 v[182:185], v148 offset:2048
	ds_read_b128 v[186:189], v148 offset:3072
	ds_read_b128 v[190:193], v148 offset:4096
	ds_read_b128 v[194:197], v148 offset:5120
	ds_read_b128 v[198:201], v148 offset:6144
	ds_read_b128 v[202:205], v148 offset:7168
	s_nop 0
	global_load_lds_dwordx4 v138, s[40:41]
	s_add_i32 m0, s47, 0xe000
	s_nop 0
	global_load_lds_dwordx4 v128, s[40:41]
	s_and_b64 vcc, exec, s[16:17]
	s_cbranch_vccnz .Lmy_lw_13
	s_waitcnt vmcnt(8)
